# static s_setprio 1 for waves 4-7 during the prompt attention unit (reset at the unit's closing barrier)
# baseline (speedup 1.0000x reference)
.LBB0_1034:
	s_lshr_b32 s98, s84, 6
	s_cmp_lt_u32 s98, 4
	s_cbranch_scc1 .Lprio9_skip
	s_setprio 1

.LBB0_1063:
	v_add_f32_e32 v4, v64, v65
	v_add_f32_e32 v4, v66, v4
	v_add_f32_e32 v4, v67, v4
	v_add_f32_e32 v4, v68, v4
	v_add_f32_e32 v4, v69, v4
	v_add_f32_e32 v4, v70, v4
	v_add_f32_e32 v4, v71, v4
	v_add_f32_e32 v4, v72, v4
	v_add_f32_e32 v4, v73, v4
	v_add_f32_e32 v4, v74, v4
	v_add_f32_e32 v4, v75, v4
	v_add_f32_e32 v4, v76, v4
	v_add_f32_e32 v4, v77, v4
	v_add_f32_e32 v4, v78, v4
	v_add_f32_e32 v4, v79, v4
	v_add_f32_e32 v4, v48, v4
	v_add_f32_e32 v4, v49, v4
	v_add_f32_e32 v4, v50, v4
	v_add_f32_e32 v4, v51, v4
	v_add_f32_e32 v4, v52, v4
	v_add_f32_e32 v4, v53, v4
	v_add_f32_e32 v4, v54, v4
	v_add_f32_e32 v4, v55, v4
	v_add_f32_e32 v4, v56, v4
	v_add_f32_e32 v4, v57, v4
	v_add_f32_e32 v4, v58, v4
	v_add_f32_e32 v4, v59, v4
	v_add_f32_e32 v4, v60, v4
	s_cmp_lg_u32 0, -1
	v_add_f32_e32 v4, v61, v4
	s_cselect_b32 s4, 0, 0
	v_add_f32_e32 v4, v62, v4
	s_addk_i32 s4, 0x6000
	v_add_f32_e32 v4, v63, v4
	v_add3_u32 v3, v212, s4, v209
	v_add_f32_e32 v0, v0, v4
	v_cvt_pk_bf16_f32 v4, v64, v65
	v_cvt_pk_bf16_f32 v5, v66, v67
	v_cvt_pk_bf16_f32 v6, v68, v69
	v_cvt_pk_bf16_f32 v7, v70, v71
	v_cvt_pk_bf16_f32 v8, v72, v73
	v_cvt_pk_bf16_f32 v9, v74, v75
	v_cvt_pk_bf16_f32 v10, v76, v77
	v_cvt_pk_bf16_f32 v11, v78, v79
	v_cvt_pk_bf16_f32 v12, v48, v49
	v_cvt_pk_bf16_f32 v13, v50, v51
	v_cvt_pk_bf16_f32 v14, v52, v53
	v_cvt_pk_bf16_f32 v15, v54, v55
	v_cvt_pk_bf16_f32 v48, v56, v57
	v_cvt_pk_bf16_f32 v49, v58, v59
	v_cvt_pk_bf16_f32 v50, v60, v61
	v_cvt_pk_bf16_f32 v51, v62, v63
	v_add3_u32 v3, v3, v210, s89
	ds_read_b64_tr_b16 v[52:53],v3 offset:0
	ds_read_b64_tr_b16 v[54:55],v3 offset:512
	ds_read_b64_tr_b16 v[56:57],v3 offset:1024
	ds_read_b64_tr_b16 v[58:59],v3 offset:1536
	ds_read_b64_tr_b16 v[60:61],v3 offset:2048
	ds_read_b64_tr_b16 v[62:63],v3 offset:2560
	ds_read_b64_tr_b16 v[64:65],v3 offset:3072
	ds_read_b64_tr_b16 v[66:67],v3 offset:3584
	s_waitcnt lgkmcnt(0)
	s_nop 0
	v_mfma_f32_32x32x16_bf16 v[32:47], v[4:7], v[52:55], v[32:47]
	ds_read_b64_tr_b16 v[52:53],v3 offset:4096
	ds_read_b64_tr_b16 v[54:55],v3 offset:4608
	v_mfma_f32_32x32x16_bf16 v[32:47], v[8:11], v[56:59], v[32:47]
	ds_read_b64_tr_b16 v[56:57],v3 offset:5120
	ds_read_b64_tr_b16 v[58:59],v3 offset:5632
	v_mfma_f32_32x32x16_bf16 v[32:47], v[12:15], v[60:63], v[32:47]
	ds_read_b64_tr_b16 v[60:61],v3 offset:6144
	ds_read_b64_tr_b16 v[62:63],v3 offset:6656
	ds_read_b64_tr_b16 v[68:69],v3 offset:7168
	ds_read_b64_tr_b16 v[70:71],v3 offset:7680
	s_waitcnt lgkmcnt(0)
	v_mfma_f32_32x32x16_bf16 v[32:47], v[48:51], v[64:67], v[32:47]
	v_mfma_f32_32x32x16_bf16 v[16:31], v[4:7], v[52:55], v[16:31]
	v_mov_b32_e32 v3, v0
	s_nop 1
	v_permlane32_swap_b32_e32 v0, v3
	v_cmp_gt_u32_e32 vcc, 32, v205
	v_mfma_f32_32x32x16_bf16 v[16:31], v[8:11], v[56:59], v[16:31]
	v_mfma_f32_32x32x16_bf16 v[16:31], v[12:15], v[60:63], v[16:31]
	v_mfma_f32_32x32x16_bf16 v[16:31], v[48:51], v[68:71], v[16:31]
	s_and_saveexec_b64 s[4:5], vcc
	v_add_f32_e32 v0, v0, v3
	ds_write_b32 v213, v0 offset:49280
	s_or_b64 exec, exec, s[4:5]
	s_waitcnt lgkmcnt(0)
	ds_read_b128 v[4:7], v2 offset:49280
	ds_read_b128 v[8:11], v2 offset:49312
	s_lshl_b32 s4, s83, 12
	s_add_i32 s4, s4, 0
	v_lshlrev_b32_e32 v50, 9, v208
	s_waitcnt lgkmcnt(1)
	v_rcp_f32_e32 v0, v4
	v_rcp_f32_e32 v3, v5
	v_rcp_f32_e32 v12, v6
	v_rcp_f32_e32 v13, v7
	s_waitcnt lgkmcnt(0)
	v_rcp_f32_e32 v14, v8
	ds_read_b128 v[4:7], v2 offset:49344
	v_rcp_f32_e32 v15, v9
	v_rcp_f32_e32 v48, v10
	v_rcp_f32_e32 v49, v11
	ds_read_b128 v[8:11], v2 offset:49376
	s_waitcnt lgkmcnt(1)
	v_rcp_f32_e32 v2, v4
	v_rcp_f32_e32 v4, v5
	v_rcp_f32_e32 v5, v6
	v_rcp_f32_e32 v6, v7
	s_waitcnt lgkmcnt(0)
	v_rcp_f32_e32 v7, v8
	v_rcp_f32_e32 v8, v9
	v_rcp_f32_e32 v9, v10
	v_rcp_f32_e32 v10, v11
	v_lshlrev_b32_e32 v11, 1, v207
	v_mul_f32_e32 v32, v32, v0
	v_mul_f32_e32 v0, v16, v0
	v_add3_u32 v11, s4, v11, v50
	v_cvt_pk_bf16_f32 v0, v0, s0
	ds_write_b16 v11, v0 offset:51264
	v_mul_f32_e32 v0, v33, v3
	v_cvt_pk_bf16_f32 v0, v0, s0
	ds_write_b16 v11, v0 offset:51328
	v_mul_f32_e32 v0, v17, v3
	v_cvt_pk_bf16_f32 v0, v0, s0
	ds_write_b16 v11, v0 offset:51392
	v_mul_f32_e32 v0, v34, v12
	v_cvt_pk_bf16_f32 v0, v0, s0
	ds_write_b16 v11, v0 offset:51456
	v_mul_f32_e32 v0, v18, v12
	v_cvt_pk_bf16_f32 v0, v0, s0
	ds_write_b16 v11, v0 offset:51520
	v_mul_f32_e32 v0, v35, v13
	v_cvt_pk_bf16_f32 v0, v0, s0
	ds_write_b16 v11, v0 offset:51584
	v_mul_f32_e32 v0, v19, v13
	v_cvt_pk_bf16_f32 v0, v0, s0
	ds_write_b16 v11, v0 offset:51648
	v_mul_f32_e32 v0, v36, v14
	v_cvt_pk_bf16_f32 v0, v0, s0
	ds_write_b16 v11, v0 offset:52224
	v_mul_f32_e32 v0, v20, v14
	v_cvt_pk_bf16_f32 v0, v0, s0
	ds_write_b16 v11, v0 offset:52288
	v_mul_f32_e32 v0, v37, v15
	v_cvt_pk_bf16_f32 v0, v0, s0
	ds_write_b16 v11, v0 offset:52352
	v_mul_f32_e32 v0, v21, v15
	v_cvt_pk_bf16_f32 v0, v0, s0
	ds_write_b16 v11, v0 offset:52416
	v_mul_f32_e32 v0, v38, v48
	v_cvt_pk_bf16_f32 v0, v0, s0
	ds_write_b16 v11, v0 offset:52480
	v_mul_f32_e32 v0, v22, v48
	v_cvt_pk_bf16_f32 v0, v0, s0
	ds_write_b16 v11, v0 offset:52544
	v_mul_f32_e32 v0, v39, v49
	v_cvt_pk_bf16_f32 v0, v0, s0
	ds_write_b16 v11, v0 offset:52608
	v_mul_f32_e32 v0, v23, v49
	v_cvt_pk_bf16_f32 v0, v0, s0
	ds_write_b16 v11, v0 offset:52672
	v_mul_f32_e32 v0, v40, v2
	v_cvt_pk_bf16_f32 v0, v0, s0
	ds_write_b16 v11, v0 offset:53248
	v_mul_f32_e32 v0, v24, v2
	v_cvt_pk_bf16_f32 v0, v0, s0
	ds_write_b16 v11, v0 offset:53312
	v_mul_f32_e32 v0, v41, v4
	v_cvt_pk_bf16_f32 v0, v0, s0
	ds_write_b16 v11, v0 offset:53376
	v_mul_f32_e32 v0, v25, v4
	v_cvt_pk_bf16_f32 v0, v0, s0
	ds_write_b16 v11, v0 offset:53440
	v_mul_f32_e32 v0, v42, v5
	v_cvt_pk_bf16_f32 v0, v0, s0
	ds_write_b16 v11, v0 offset:53504
	v_mul_f32_e32 v0, v26, v5
	v_cvt_pk_bf16_f32 v0, v0, s0
	ds_write_b16 v11, v0 offset:53568
	v_mul_f32_e32 v0, v43, v6
	v_cvt_pk_bf16_f32 v0, v0, s0
	ds_write_b16 v11, v0 offset:53632
	v_mul_f32_e32 v0, v27, v6
	v_cvt_pk_bf16_f32 v0, v0, s0
	ds_write_b16 v11, v0 offset:53696
	v_mul_f32_e32 v0, v44, v7
	v_cvt_pk_bf16_f32 v0, v0, s0
	ds_write_b16 v11, v0 offset:54272
	v_mul_f32_e32 v0, v28, v7
	v_cvt_pk_bf16_f32 v0, v0, s0
	ds_write_b16 v11, v0 offset:54336
	v_mul_f32_e32 v0, v45, v8
	v_cvt_pk_bf16_f32 v0, v0, s0
	ds_write_b16 v11, v0 offset:54400
	v_mul_f32_e32 v0, v29, v8
	v_cvt_pk_bf16_f32 v0, v0, s0
	ds_write_b16 v11, v0 offset:54464
	v_mul_f32_e32 v0, v46, v9
	v_cvt_pk_bf16_f32 v0, v0, s0
	ds_write_b16 v11, v0 offset:54528
	v_mul_f32_e32 v0, v30, v9
	v_cvt_pk_bf16_f32 v0, v0, s0
	ds_write_b16 v11, v0 offset:54592
	v_mul_f32_e32 v0, v47, v10
	v_cvt_pk_bf16_f32 v0, v0, s0
	ds_write_b16 v11, v0 offset:54656
	v_mul_f32_e32 v0, v31, v10
	v_cvt_pk_bf16_f32 v0, v0, s0
	ds_write_b16 v11, v0 offset:54720
	v_lshlrev_b32_e32 v0, 1, v206
	v_cvt_pk_bf16_f32 v32, v32, s0
	v_and_b32_e32 v0, 0x70, v0
	ds_write_b16 v11, v32 offset:51200
	v_lshrrev_b32_e32 v14, 3, v205
	v_add_u32_e32 v15, s4, v0
	s_waitcnt lgkmcnt(0)
	v_lshl_add_u64 v[10:11], s[30:31], 0, v[0:1]
	v_lshl_add_u32 v0, v14, 7, v15
	v_or_b32_e32 v16, 8, v14
	ds_read_b128 v[2:5], v0 offset:51200
	v_lshl_add_u32 v6, v16, 7, v15
	ds_read_b128 v[6:9], v6 offset:51200
	v_lshlrev_b32_e32 v0, 11, v14
	v_lshl_add_u64 v[12:13], v[10:11], 0, v[0:1]
	v_lshlrev_b32_e32 v0, 11, v16
	s_waitcnt lgkmcnt(1)
	global_store_dwordx4 v[12:13], v[2:5], off
	s_nop 1
	v_lshl_add_u64 v[2:3], v[10:11], 0, v[0:1]
	v_or_b32_e32 v0, 16, v14
	s_waitcnt lgkmcnt(0)
	global_store_dwordx4 v[2:3], v[6:9], off
	v_lshl_add_u32 v2, v0, 7, v15
	v_or_b32_e32 v14, 24, v14
	ds_read_b128 v[2:5], v2 offset:51200
	v_lshl_add_u32 v6, v14, 7, v15
	ds_read_b128 v[6:9], v6 offset:51200
	v_lshlrev_b32_e32 v0, 11, v0
	v_lshl_add_u64 v[12:13], v[10:11], 0, v[0:1]
	v_lshlrev_b32_e32 v0, 11, v14
	s_waitcnt lgkmcnt(1)
	global_store_dwordx4 v[12:13], v[2:5], off
	s_nop 1
	v_lshl_add_u64 v[2:3], v[10:11], 0, v[0:1]
	s_waitcnt lgkmcnt(0)
	global_store_dwordx4 v[2:3], v[6:9], off
	s_waitcnt lgkmcnt(0)
	s_barrier
	s_setprio 0
	s_and_b64 vcc, exec, s[28:29]
	s_cbranch_vccz .LBB0_922
